# F leftover stage: idle workgroups convert at most 4 PEER table pairs (was unlimited), the remainder is shared by all 256 in the drain
# baseline (speedup 1.0000x reference)
.LBB0_869:
	s_mul_i32 s33, s33, s70
	s_sub_i32 s26, 0x420, s33
	s_lshl_b32 s27, s26, 2
	s_cmp_lt_i32 s2, s27
	s_cselect_b64 s[4:5], -1, 0
	s_cmp_lt_i32 s88, s26
	s_cselect_b64 s[12:13], -1, 0
	s_and_b64 s[4:5], s[12:13], s[4:5]
	s_and_b64 vcc, exec, s[4:5]
	s_cbranch_vccnz .LBB0_885
	s_waitcnt lgkmcnt(0)
	s_add_u32 s12, s6, 0x1a21c0
	s_addc_u32 s13, s7, 0
	s_add_u32 s14, s6, 0x1d27000
	s_addc_u32 s15, s7, 0
	s_mov_b64 s[4:5], src_shared_base
	v_mov_b32_e32 v0, v176
	s_add_u32 s16, s6, 0xd27000
	s_addc_u32 s17, s7, 0
	v_ashrrev_i32_e32 v42, 8, v0
	s_mov_b32 s28, 4
	s_mov_b64 s[18:19], 0
	v_mov_b32_e32 v33, 0
	v_mov_b32_e32 v34, 0x24000
	v_mov_b32_e32 v37, s5
	v_mov_b32_e32 v36, 0x24000
	s_movk_i32 s29, 0x800
	s_movk_i32 s30, 0x7ff
	s_movk_i32 s31, 0xc000
	s_movk_i32 s33, 0x300
	s_branch .LBB0_873
